# P5 epilogue hand-rewritten: x loads as 4 groups with 3 in flight, batched cross-lane reduction, atomics last, no validity scaffolding
# speedup vs baseline: 1.0118x; 1.0048x over previous
.LBB0_674:
	v_cmp_eq_u32_e32 vcc, 0, v130
	s_cbranch_vccnz .LBB0_756
	v_lshl_add_u32 v193, s6, 8, v195
	v_lshl_or_b32 v227, s4, 8, v221
	v_lshlrev_b32_e32 v131, 12, v193
	v_lshlrev_b32_e32 v192, 11, v193
	v_lshl_add_u32 v131, v227, 2, v131
	v_lshl_add_u32 v192, v227, 1, v192
	v_lshlrev_b32_e32 v193, 2, v193
	v_mov_b32_e32 v244, v131
	global_load_dwordx4 v[132:135], v244, s[80:81] nt
	global_load_dwordx4 v[136:139], v244, s[80:81] offset:16 nt
	global_load_dwordx4 v[140:143], v244, s[80:81] offset:512 nt
	global_load_dwordx4 v[144:147], v244, s[80:81] offset:528 nt
	v_add_u32_e32 v244, 0x10000, v131
	global_load_dwordx4 v[148:151], v244, s[80:81] nt
	global_load_dwordx4 v[152:155], v244, s[80:81] offset:16 nt
	global_load_dwordx4 v[156:159], v244, s[80:81] offset:512 nt
	global_load_dwordx4 v[160:163], v244, s[80:81] offset:528 nt
	v_add_u32_e32 v244, 0x20000, v131
	global_load_dwordx4 v[164:167], v244, s[80:81] nt
	global_load_dwordx4 v[168:171], v244, s[80:81] offset:16 nt
	global_load_dwordx4 v[172:175], v244, s[80:81] offset:512 nt
	global_load_dwordx4 v[176:179], v244, s[80:81] offset:528 nt
	v_add_u32_e32 v244, 0x30000, v131
	global_load_dwordx4 v[180:183], v244, s[80:81] nt
	global_load_dwordx4 v[184:187], v244, s[80:81] offset:16 nt
	global_load_dwordx4 v[188:191], v244, s[80:81] offset:512 nt
	global_load_dwordx4 v[208:211], v244, s[80:81] offset:528 nt
	v_add_u32_e32 v244, 0x80000, v131
	global_load_dwordx4 v[212:215], v244, s[80:81] nt
	global_load_dwordx4 v[216:219], v244, s[80:81] offset:16 nt
	global_load_dwordx4 v[228:231], v244, s[80:81] offset:512 nt
	global_load_dwordx4 v[232:235], v244, s[80:81] offset:528 nt
	v_add_u32_e32 v244, 0x90000, v131
	global_load_dwordx4 v[236:239], v244, s[80:81] nt
	global_load_dwordx4 v[240:243], v244, s[80:81] offset:16 nt
	global_load_dwordx4 v[248:251], v244, s[80:81] offset:512 nt
	global_load_dwordx4 v[252:255], v244, s[80:81] offset:528 nt
	s_waitcnt vmcnt(16)
	v_pk_add_f32 v[126:127], v[126:127], v[132:133]
	v_pk_add_f32 v[128:129], v[128:129], v[134:135]
	v_pk_add_f32 v[122:123], v[122:123], v[136:137]
	v_pk_add_f32 v[124:125], v[124:125], v[138:139]
	v_pk_add_f32 v[118:119], v[118:119], v[140:141]
	v_pk_add_f32 v[120:121], v[120:121], v[142:143]
	v_pk_add_f32 v[114:115], v[114:115], v[144:145]
	v_pk_add_f32 v[116:117], v[116:117], v[146:147]
	v_mul_f32_e32 v227, v127, v127
	v_fmac_f32_e32 v227, v126, v126
	v_mul_f32_e32 v244, v129, v129
	v_fmac_f32_e32 v244, v128, v128
	v_add_f32_e32 v227, v227, v244
	v_mul_f32_e32 v244, v123, v123
	v_fmac_f32_e32 v244, v122, v122
	v_add_f32_e32 v227, v227, v244
	v_mul_f32_e32 v244, v125, v125
	v_fmac_f32_e32 v244, v124, v124
	v_add_f32_e32 v227, v227, v244
	v_mul_f32_e32 v245, v119, v119
	v_fmac_f32_e32 v245, v118, v118
	v_mul_f32_e32 v244, v121, v121
	v_fmac_f32_e32 v244, v120, v120
	v_add_f32_e32 v245, v245, v244
	v_mul_f32_e32 v244, v115, v115
	v_fmac_f32_e32 v244, v114, v114
	v_add_f32_e32 v245, v245, v244
	v_mul_f32_e32 v244, v117, v117
	v_fmac_f32_e32 v244, v116, v116
	v_add_f32_e32 v245, v245, v244
	v_cvt_pk_bf16_f32 v126, v126, v127
	v_cvt_pk_bf16_f32 v127, v128, v129
	v_cvt_pk_bf16_f32 v128, v122, v123
	v_cvt_pk_bf16_f32 v129, v124, v125
	v_cvt_pk_bf16_f32 v118, v118, v119
	v_cvt_pk_bf16_f32 v119, v120, v121
	v_cvt_pk_bf16_f32 v120, v114, v115
	v_cvt_pk_bf16_f32 v121, v116, v117
	v_add_f32_e32 v122, v227, v245
	v_mov_b32_e32 v244, v192
	global_store_dwordx4 v244, v[126:129], s[96:97]
	global_store_dwordx4 v244, v[118:121], s[96:97] offset:256
	v_pk_add_f32 v[110:111], v[110:111], v[148:149]
	v_pk_add_f32 v[112:113], v[112:113], v[150:151]
	v_pk_add_f32 v[106:107], v[106:107], v[152:153]
	v_pk_add_f32 v[108:109], v[108:109], v[154:155]
	v_pk_add_f32 v[102:103], v[102:103], v[156:157]
	v_pk_add_f32 v[104:105], v[104:105], v[158:159]
	v_pk_add_f32 v[98:99], v[98:99], v[160:161]
	v_pk_add_f32 v[100:101], v[100:101], v[162:163]
	v_mul_f32_e32 v227, v111, v111
	v_fmac_f32_e32 v227, v110, v110
	v_mul_f32_e32 v244, v113, v113
	v_fmac_f32_e32 v244, v112, v112
	v_add_f32_e32 v227, v227, v244
	v_mul_f32_e32 v244, v107, v107
	v_fmac_f32_e32 v244, v106, v106
	v_add_f32_e32 v227, v227, v244
	v_mul_f32_e32 v244, v109, v109
	v_fmac_f32_e32 v244, v108, v108
	v_add_f32_e32 v227, v227, v244
	v_mul_f32_e32 v245, v103, v103
	v_fmac_f32_e32 v245, v102, v102
	v_mul_f32_e32 v244, v105, v105
	v_fmac_f32_e32 v244, v104, v104
	v_add_f32_e32 v245, v245, v244
	v_mul_f32_e32 v244, v99, v99
	v_fmac_f32_e32 v244, v98, v98
	v_add_f32_e32 v245, v245, v244
	v_mul_f32_e32 v244, v101, v101
	v_fmac_f32_e32 v244, v100, v100
	v_add_f32_e32 v245, v245, v244
	v_cvt_pk_bf16_f32 v110, v110, v111
	v_cvt_pk_bf16_f32 v111, v112, v113
	v_cvt_pk_bf16_f32 v112, v106, v107
	v_cvt_pk_bf16_f32 v113, v108, v109
	v_cvt_pk_bf16_f32 v102, v102, v103
	v_cvt_pk_bf16_f32 v103, v104, v105
	v_cvt_pk_bf16_f32 v104, v98, v99
	v_cvt_pk_bf16_f32 v105, v100, v101
	v_add_f32_e32 v106, v227, v245
	v_add_u32_e32 v244, 0x8000, v192
	global_store_dwordx4 v244, v[110:113], s[96:97]
	global_store_dwordx4 v244, v[102:105], s[96:97] offset:256
	v_add_u32_e32 v244, 0xa0000, v131
	global_load_dwordx4 v[132:135], v244, s[80:81] nt
	global_load_dwordx4 v[136:139], v244, s[80:81] offset:16 nt
	global_load_dwordx4 v[140:143], v244, s[80:81] offset:512 nt
	global_load_dwordx4 v[144:147], v244, s[80:81] offset:528 nt
	v_add_u32_e32 v244, 0xb0000, v131
	global_load_dwordx4 v[148:151], v244, s[80:81] nt
	global_load_dwordx4 v[152:155], v244, s[80:81] offset:16 nt
	global_load_dwordx4 v[156:159], v244, s[80:81] offset:512 nt
	global_load_dwordx4 v[160:163], v244, s[80:81] offset:528 nt
	s_waitcnt vmcnt(20)
	v_pk_add_f32 v[94:95], v[94:95], v[164:165]
	v_pk_add_f32 v[96:97], v[96:97], v[166:167]
	v_pk_add_f32 v[90:91], v[90:91], v[168:169]
	v_pk_add_f32 v[92:93], v[92:93], v[170:171]
	v_pk_add_f32 v[86:87], v[86:87], v[172:173]
	v_pk_add_f32 v[88:89], v[88:89], v[174:175]
	v_pk_add_f32 v[82:83], v[82:83], v[176:177]
	v_pk_add_f32 v[84:85], v[84:85], v[178:179]
	v_mul_f32_e32 v227, v95, v95
	v_fmac_f32_e32 v227, v94, v94
	v_mul_f32_e32 v244, v97, v97
	v_fmac_f32_e32 v244, v96, v96
	v_add_f32_e32 v227, v227, v244
	v_mul_f32_e32 v244, v91, v91
	v_fmac_f32_e32 v244, v90, v90
	v_add_f32_e32 v227, v227, v244
	v_mul_f32_e32 v244, v93, v93
	v_fmac_f32_e32 v244, v92, v92
	v_add_f32_e32 v227, v227, v244
	v_mul_f32_e32 v245, v87, v87
	v_fmac_f32_e32 v245, v86, v86
	v_mul_f32_e32 v244, v89, v89
	v_fmac_f32_e32 v244, v88, v88
	v_add_f32_e32 v245, v245, v244
	v_mul_f32_e32 v244, v83, v83
	v_fmac_f32_e32 v244, v82, v82
	v_add_f32_e32 v245, v245, v244
	v_mul_f32_e32 v244, v85, v85
	v_fmac_f32_e32 v244, v84, v84
	v_add_f32_e32 v245, v245, v244
	v_cvt_pk_bf16_f32 v94, v94, v95
	v_cvt_pk_bf16_f32 v95, v96, v97
	v_cvt_pk_bf16_f32 v96, v90, v91
	v_cvt_pk_bf16_f32 v97, v92, v93
	v_cvt_pk_bf16_f32 v86, v86, v87
	v_cvt_pk_bf16_f32 v87, v88, v89
	v_cvt_pk_bf16_f32 v88, v82, v83
	v_cvt_pk_bf16_f32 v89, v84, v85
	v_add_f32_e32 v90, v227, v245
	v_add_u32_e32 v244, 0x10000, v192
	global_store_dwordx4 v244, v[94:97], s[96:97]
	global_store_dwordx4 v244, v[86:89], s[96:97] offset:256
	v_pk_add_f32 v[78:79], v[78:79], v[180:181]
	v_pk_add_f32 v[80:81], v[80:81], v[182:183]
	v_pk_add_f32 v[74:75], v[74:75], v[184:185]
	v_pk_add_f32 v[76:77], v[76:77], v[186:187]
	v_pk_add_f32 v[70:71], v[70:71], v[188:189]
	v_pk_add_f32 v[72:73], v[72:73], v[190:191]
	v_pk_add_f32 v[66:67], v[66:67], v[208:209]
	v_pk_add_f32 v[68:69], v[68:69], v[210:211]
	v_mul_f32_e32 v227, v79, v79
	v_fmac_f32_e32 v227, v78, v78
	v_mul_f32_e32 v244, v81, v81
	v_fmac_f32_e32 v244, v80, v80
	v_add_f32_e32 v227, v227, v244
	v_mul_f32_e32 v244, v75, v75
	v_fmac_f32_e32 v244, v74, v74
	v_add_f32_e32 v227, v227, v244
	v_mul_f32_e32 v244, v77, v77
	v_fmac_f32_e32 v244, v76, v76
	v_add_f32_e32 v227, v227, v244
	v_mul_f32_e32 v245, v71, v71
	v_fmac_f32_e32 v245, v70, v70
	v_mul_f32_e32 v244, v73, v73
	v_fmac_f32_e32 v244, v72, v72
	v_add_f32_e32 v245, v245, v244
	v_mul_f32_e32 v244, v67, v67
	v_fmac_f32_e32 v244, v66, v66
	v_add_f32_e32 v245, v245, v244
	v_mul_f32_e32 v244, v69, v69
	v_fmac_f32_e32 v244, v68, v68
	v_add_f32_e32 v245, v245, v244
	v_cvt_pk_bf16_f32 v78, v78, v79
	v_cvt_pk_bf16_f32 v79, v80, v81
	v_cvt_pk_bf16_f32 v80, v74, v75
	v_cvt_pk_bf16_f32 v81, v76, v77
	v_cvt_pk_bf16_f32 v70, v70, v71
	v_cvt_pk_bf16_f32 v71, v72, v73
	v_cvt_pk_bf16_f32 v72, v66, v67
	v_cvt_pk_bf16_f32 v73, v68, v69
	v_add_f32_e32 v74, v227, v245
	v_add_u32_e32 v244, 0x18000, v192
	global_store_dwordx4 v244, v[78:81], s[96:97]
	global_store_dwordx4 v244, v[70:73], s[96:97] offset:256
	s_waitcnt vmcnt(16)
	v_pk_add_f32 v[62:63], v[62:63], v[212:213]
	v_pk_add_f32 v[64:65], v[64:65], v[214:215]
	v_pk_add_f32 v[58:59], v[58:59], v[216:217]
	v_pk_add_f32 v[60:61], v[60:61], v[218:219]
	v_pk_add_f32 v[54:55], v[54:55], v[228:229]
	v_pk_add_f32 v[56:57], v[56:57], v[230:231]
	v_pk_add_f32 v[50:51], v[50:51], v[232:233]
	v_pk_add_f32 v[52:53], v[52:53], v[234:235]
	v_mul_f32_e32 v227, v63, v63
	v_fmac_f32_e32 v227, v62, v62
	v_mul_f32_e32 v244, v65, v65
	v_fmac_f32_e32 v244, v64, v64
	v_add_f32_e32 v227, v227, v244
	v_mul_f32_e32 v244, v59, v59
	v_fmac_f32_e32 v244, v58, v58
	v_add_f32_e32 v227, v227, v244
	v_mul_f32_e32 v244, v61, v61
	v_fmac_f32_e32 v244, v60, v60
	v_add_f32_e32 v227, v227, v244
	v_mul_f32_e32 v245, v55, v55
	v_fmac_f32_e32 v245, v54, v54
	v_mul_f32_e32 v244, v57, v57
	v_fmac_f32_e32 v244, v56, v56
	v_add_f32_e32 v245, v245, v244
	v_mul_f32_e32 v244, v51, v51
	v_fmac_f32_e32 v244, v50, v50
	v_add_f32_e32 v245, v245, v244
	v_mul_f32_e32 v244, v53, v53
	v_fmac_f32_e32 v244, v52, v52
	v_add_f32_e32 v245, v245, v244
	v_cvt_pk_bf16_f32 v62, v62, v63
	v_cvt_pk_bf16_f32 v63, v64, v65
	v_cvt_pk_bf16_f32 v64, v58, v59
	v_cvt_pk_bf16_f32 v65, v60, v61
	v_cvt_pk_bf16_f32 v54, v54, v55
	v_cvt_pk_bf16_f32 v55, v56, v57
	v_cvt_pk_bf16_f32 v56, v50, v51
	v_cvt_pk_bf16_f32 v57, v52, v53
	v_add_f32_e32 v58, v227, v245
	v_add_u32_e32 v244, 0x40000, v192
	global_store_dwordx4 v244, v[62:65], s[96:97]
	global_store_dwordx4 v244, v[54:57], s[96:97] offset:256
	v_pk_add_f32 v[46:47], v[46:47], v[236:237]
	v_pk_add_f32 v[48:49], v[48:49], v[238:239]
	v_pk_add_f32 v[42:43], v[42:43], v[240:241]
	v_pk_add_f32 v[44:45], v[44:45], v[242:243]
	v_pk_add_f32 v[38:39], v[38:39], v[248:249]
	v_pk_add_f32 v[40:41], v[40:41], v[250:251]
	v_pk_add_f32 v[34:35], v[34:35], v[252:253]
	v_pk_add_f32 v[36:37], v[36:37], v[254:255]
	v_mul_f32_e32 v227, v47, v47
	v_fmac_f32_e32 v227, v46, v46
	v_mul_f32_e32 v244, v49, v49
	v_fmac_f32_e32 v244, v48, v48
	v_add_f32_e32 v227, v227, v244
	v_mul_f32_e32 v244, v43, v43
	v_fmac_f32_e32 v244, v42, v42
	v_add_f32_e32 v227, v227, v244
	v_mul_f32_e32 v244, v45, v45
	v_fmac_f32_e32 v244, v44, v44
	v_add_f32_e32 v227, v227, v244
	v_mul_f32_e32 v245, v39, v39
	v_fmac_f32_e32 v245, v38, v38
	v_mul_f32_e32 v244, v41, v41
	v_fmac_f32_e32 v244, v40, v40
	v_add_f32_e32 v245, v245, v244
	v_mul_f32_e32 v244, v35, v35
	v_fmac_f32_e32 v244, v34, v34
	v_add_f32_e32 v245, v245, v244
	v_mul_f32_e32 v244, v37, v37
	v_fmac_f32_e32 v244, v36, v36
	v_add_f32_e32 v245, v245, v244
	v_cvt_pk_bf16_f32 v46, v46, v47
	v_cvt_pk_bf16_f32 v47, v48, v49
	v_cvt_pk_bf16_f32 v48, v42, v43
	v_cvt_pk_bf16_f32 v49, v44, v45
	v_cvt_pk_bf16_f32 v38, v38, v39
	v_cvt_pk_bf16_f32 v39, v40, v41
	v_cvt_pk_bf16_f32 v40, v34, v35
	v_cvt_pk_bf16_f32 v41, v36, v37
	v_add_f32_e32 v42, v227, v245
	v_add_u32_e32 v244, 0x48000, v192
	global_store_dwordx4 v244, v[46:49], s[96:97]
	global_store_dwordx4 v244, v[38:41], s[96:97] offset:256
	s_waitcnt vmcnt(8)
	v_pk_add_f32 v[30:31], v[30:31], v[132:133]
	v_pk_add_f32 v[32:33], v[32:33], v[134:135]
	v_pk_add_f32 v[26:27], v[26:27], v[136:137]
	v_pk_add_f32 v[28:29], v[28:29], v[138:139]
	v_pk_add_f32 v[22:23], v[22:23], v[140:141]
	v_pk_add_f32 v[24:25], v[24:25], v[142:143]
	v_pk_add_f32 v[18:19], v[18:19], v[144:145]
	v_pk_add_f32 v[20:21], v[20:21], v[146:147]
	v_mul_f32_e32 v227, v31, v31
	v_fmac_f32_e32 v227, v30, v30
	v_mul_f32_e32 v244, v33, v33
	v_fmac_f32_e32 v244, v32, v32
	v_add_f32_e32 v227, v227, v244
	v_mul_f32_e32 v244, v27, v27
	v_fmac_f32_e32 v244, v26, v26
	v_add_f32_e32 v227, v227, v244
	v_mul_f32_e32 v244, v29, v29
	v_fmac_f32_e32 v244, v28, v28
	v_add_f32_e32 v227, v227, v244
	v_mul_f32_e32 v245, v23, v23
	v_fmac_f32_e32 v245, v22, v22
	v_mul_f32_e32 v244, v25, v25
	v_fmac_f32_e32 v244, v24, v24
	v_add_f32_e32 v245, v245, v244
	v_mul_f32_e32 v244, v19, v19
	v_fmac_f32_e32 v244, v18, v18
	v_add_f32_e32 v245, v245, v244
	v_mul_f32_e32 v244, v21, v21
	v_fmac_f32_e32 v244, v20, v20
	v_add_f32_e32 v245, v245, v244
	v_cvt_pk_bf16_f32 v30, v30, v31
	v_cvt_pk_bf16_f32 v31, v32, v33
	v_cvt_pk_bf16_f32 v32, v26, v27
	v_cvt_pk_bf16_f32 v33, v28, v29
	v_cvt_pk_bf16_f32 v22, v22, v23
	v_cvt_pk_bf16_f32 v23, v24, v25
	v_cvt_pk_bf16_f32 v24, v18, v19
	v_cvt_pk_bf16_f32 v25, v20, v21
	v_add_f32_e32 v26, v227, v245
	v_add_u32_e32 v244, 0x50000, v192
	global_store_dwordx4 v244, v[30:33], s[96:97]
	global_store_dwordx4 v244, v[22:25], s[96:97] offset:256
	v_pk_add_f32 v[14:15], v[14:15], v[148:149]
	v_pk_add_f32 v[16:17], v[16:17], v[150:151]
	v_pk_add_f32 v[10:11], v[10:11], v[152:153]
	v_pk_add_f32 v[12:13], v[12:13], v[154:155]
	v_pk_add_f32 v[6:7], v[6:7], v[156:157]
	v_pk_add_f32 v[8:9], v[8:9], v[158:159]
	v_pk_add_f32 v[2:3], v[2:3], v[160:161]
	v_pk_add_f32 v[4:5], v[4:5], v[162:163]
	v_mul_f32_e32 v227, v15, v15
	v_fmac_f32_e32 v227, v14, v14
	v_mul_f32_e32 v244, v17, v17
	v_fmac_f32_e32 v244, v16, v16
	v_add_f32_e32 v227, v227, v244
	v_mul_f32_e32 v244, v11, v11
	v_fmac_f32_e32 v244, v10, v10
	v_add_f32_e32 v227, v227, v244
	v_mul_f32_e32 v244, v13, v13
	v_fmac_f32_e32 v244, v12, v12
	v_add_f32_e32 v227, v227, v244
	v_mul_f32_e32 v245, v7, v7
	v_fmac_f32_e32 v245, v6, v6
	v_mul_f32_e32 v244, v9, v9
	v_fmac_f32_e32 v244, v8, v8
	v_add_f32_e32 v245, v245, v244
	v_mul_f32_e32 v244, v3, v3
	v_fmac_f32_e32 v244, v2, v2
	v_add_f32_e32 v245, v245, v244
	v_mul_f32_e32 v244, v5, v5
	v_fmac_f32_e32 v244, v4, v4
	v_add_f32_e32 v245, v245, v244
	v_cvt_pk_bf16_f32 v14, v14, v15
	v_cvt_pk_bf16_f32 v15, v16, v17
	v_cvt_pk_bf16_f32 v16, v10, v11
	v_cvt_pk_bf16_f32 v17, v12, v13
	v_cvt_pk_bf16_f32 v6, v6, v7
	v_cvt_pk_bf16_f32 v7, v8, v9
	v_cvt_pk_bf16_f32 v8, v2, v3
	v_cvt_pk_bf16_f32 v9, v4, v5
	v_add_f32_e32 v10, v227, v245
	v_add_u32_e32 v244, 0x58000, v192
	global_store_dwordx4 v244, v[14:17], s[96:97]
	global_store_dwordx4 v244, v[6:9], s[96:97] offset:256
	v_xor_b32_e32 v126, 16, v225
	v_xor_b32_e32 v127, 32, v225
	v_lshlrev_b32_e32 v126, 2, v126
	v_lshlrev_b32_e32 v127, 2, v127
	ds_bpermute_b32 v114, v126, v122
	ds_bpermute_b32 v98, v126, v106
	ds_bpermute_b32 v82, v126, v90
	ds_bpermute_b32 v66, v126, v74
	ds_bpermute_b32 v50, v126, v58
	ds_bpermute_b32 v34, v126, v42
	ds_bpermute_b32 v18, v126, v26
	ds_bpermute_b32 v2, v126, v10
	s_waitcnt lgkmcnt(0)
	v_add_f32_e32 v122, v122, v114
	v_add_f32_e32 v106, v106, v98
	v_add_f32_e32 v90, v90, v82
	v_add_f32_e32 v74, v74, v66
	v_add_f32_e32 v58, v58, v50
	v_add_f32_e32 v42, v42, v34
	v_add_f32_e32 v26, v26, v18
	v_add_f32_e32 v10, v10, v2
	ds_bpermute_b32 v114, v127, v122
	ds_bpermute_b32 v98, v127, v106
	ds_bpermute_b32 v82, v127, v90
	ds_bpermute_b32 v66, v127, v74
	ds_bpermute_b32 v50, v127, v58
	ds_bpermute_b32 v34, v127, v42
	ds_bpermute_b32 v18, v127, v26
	ds_bpermute_b32 v2, v127, v10
	s_waitcnt lgkmcnt(0)
	v_add_f32_e32 v122, v122, v114
	v_add_f32_e32 v106, v106, v98
	v_add_f32_e32 v90, v90, v82
	v_add_f32_e32 v74, v74, v66
	v_add_f32_e32 v58, v58, v50
	v_add_f32_e32 v42, v42, v34
	v_add_f32_e32 v26, v26, v18
	v_add_f32_e32 v10, v10, v2
	s_and_saveexec_b64 s[10:11], s[0:1]
	global_atomic_add_f32 v193, v122, s[76:77]
	global_atomic_add_f32 v193, v106, s[76:77] offset:64
	global_atomic_add_f32 v193, v90, s[76:77] offset:128
	global_atomic_add_f32 v193, v74, s[76:77] offset:192
	global_atomic_add_f32 v193, v58, s[76:77] offset:512
	global_atomic_add_f32 v193, v42, s[76:77] offset:576
	global_atomic_add_f32 v193, v26, s[76:77] offset:640
	global_atomic_add_f32 v193, v10, s[76:77] offset:704
	s_or_b64 exec, exec, s[10:11]
